# GEMM phases: per-phase s_setprio flips deleted and one static s_setprio 1 for waves 4-7 per phase; on top of v112
# speedup vs baseline: 1.0049x; 1.0008x over previous
.LBB0_287:
	s_or_b64 exec, exec, s[2:3]
	s_waitcnt lgkmcnt(0)
	s_barrier
	s_getreg_b32 s100, hwreg(HW_REG_HW_ID, 0, 6)
	s_and_b32 s100, s100, 63
	s_lshl_b32 s100, s100, 2
	s_add_i32 s100, s100, 0x22ef0
	v_mov_b32_e32 v240, s100
	ds_read_b32 v240, v240
	s_waitcnt lgkmcnt(0)
	v_readfirstlane_b32 s100, v240
	s_nop 1
	s_cmp_ge_u32 s100, 4
	s_cbranch_scc0 .Lgp_3
	s_setprio 1
.Lgp_3:
	s_mov_b64 s[0:1], 0
.LBB0_288:
	s_and_b64 vcc, exec, s[0:1]
	s_cbranch_vccz .LBB0_854
	s_mov_b64 s[0:1], 0x6500000
	s_mov_b64 s[8:9], 0x5400000
	s_mov_b64 s[4:5], 0x8800000
	s_mov_b64 s[6:7], 0xe800000
	s_getreg_b32 s2, hwreg(HW_REG_HW_ID, 0, 6)
	s_and_b32 s2, s2, 63
	s_lshl_b32 s2, s2, 2
	s_add_i32 s2, s2, 0
	s_add_i32 s2, s2, 0x22ef0
	v_mov_b32_e32 v0, s2
	ds_read_b32 v0, v0
	v_readlane_b32 s10, v253, 6
	v_readlane_b32 s11, v253, 7
	s_and_b64 vcc, exec, s[10:11]
	s_waitcnt lgkmcnt(0)
	v_readfirstlane_b32 s2, v0
	v_mov_b32_e32 v0, v177
	s_nop 0
	v_mbcnt_lo_u32_b32 v0, -1, v0
	v_mbcnt_hi_u32_b32 v0, -1, v0
	v_lshl_add_u32 v14, s2, 6, v0
	s_movk_i32 s2, 0x800
	v_readfirstlane_b32 s18, v14
	s_cbranch_vccz .LBB0_313
	v_lshlrev_b32_e32 v0, 4, v14
	v_add_u32_e32 v1, 0x2000, v0
	v_ashrrev_i32_e32 v2, 31, v1
	v_lshrrev_b32_e32 v2, 22, v2
	v_add_u32_e32 v2, v1, v2
	v_ashrrev_i32_e32 v12, 10, v2
	v_mul_i32_i24_e32 v3, 0x400, v12
	v_sub_u32_e32 v1, v1, v3
	v_lshrrev_b32_e32 v3, 4, v1
	v_bitop3_b32 v1, v3, v1, 32 bitop3:0x6c
	v_ashrrev_i32_e32 v3, 31, v1
	v_lshrrev_b32_e32 v3, 26, v3
	v_add_u32_e32 v3, v1, v3
	v_ashrrev_i32_e32 v13, 6, v3
	v_and_b32_e32 v3, 0xc0, v3
	v_sub_u32_e32 v1, v1, v3
	v_mov_b32_e32 v4, 1
	v_lshlrev_b32_e32 v2, 5, v12
	v_ashrrev_i16_sdwa v1, v4, sext(v1) dst_sel:DWORD dst_unused:UNUSED_PAD src0_sel:DWORD src1_sel:BYTE_0
	v_and_b32_e32 v2, 32, v2
	v_bfe_i32 v15, v1, 0, 16
	v_add_u32_e32 v1, v2, v15
	v_lshlrev_b32_e32 v2, 3, v12
	v_and_b32_e32 v2, -16, v2
	v_add_u32_e32 v2, v13, v2
	v_mul_lo_u32 v3, v2, s2
	v_lshlrev_b32_e32 v2, 11, v2
	v_lshl_add_u32 v130, v1, 1, v2
	v_bfe_i32 v2, v14, 27, 1
	v_lshrrev_b32_e32 v2, 22, v2
	v_add_u32_e32 v2, v0, v2
	v_and_b32_e32 v2, 0xfffffc00, v2
	v_sub_u32_e32 v0, v0, v2
	v_lshrrev_b32_e32 v2, 4, v0
	v_bitop3_b32 v2, v2, v0, 32 bitop3:0x6c
	v_ashrrev_i32_e32 v0, 31, v0
	s_add_u32 s28, s66, s0
	v_lshrrev_b32_e32 v0, 26, v0
	s_addc_u32 s29, s67, s1
	v_add_lshl_u32 v128, v1, v3, 1
	v_ashrrev_i32_e32 v1, 31, v14
	v_add_u32_e32 v0, v2, v0
	s_add_u32 s30, s66, s8
	v_lshrrev_b32_e32 v1, 26, v1
	v_ashrrev_i32_e32 v17, 6, v0
	s_addc_u32 s31, s67, s9
	s_ashr_i32 s3, s2, 31
	v_add_u32_e32 v1, v14, v1
	v_mul_i32_i24_e32 v0, 64, v17
	v_readlane_b32 s16, v253, 40
	s_lshl_b64 s[12:13], s[2:3], 9
	v_ashrrev_i32_e32 v16, 6, v1
	v_sub_u32_e32 v0, v2, v0
	v_readlane_b32 s17, v253, 41
	v_lshlrev_b32_e32 v1, 5, v16
	v_ashrrev_i16_sdwa v0, v4, sext(v0) dst_sel:DWORD dst_unused:UNUSED_PAD src0_sel:DWORD src1_sel:BYTE_0
	s_mul_i32 s0, s12, s17
	s_mul_hi_u32 s1, s12, s16
	v_and_b32_e32 v1, 32, v1
	v_bfe_i32 v18, v0, 0, 16
	s_add_i32 s14, s1, s0
	s_lshr_b64 s[0:1], s[2:3], 23
	s_ashr_i32 s9, s18, 6
	v_add_u32_e32 v0, v1, v18
	v_lshlrev_b32_e32 v1, 3, v16
	s_mul_i32 s0, s0, s16
	s_ashr_i32 s8, s18, 8
	s_lshl_b64 s[10:11], s[2:3], 8
	s_lshl_b32 s33, s9, 10
	v_and_b32_e32 v1, -16, v1
	s_add_i32 s14, s14, s0
	s_mul_i32 s0, s12, s16
	v_add_u32_e32 v1, v17, v1
	s_add_u32 s26, s30, s0
	v_mul_lo_u32 v2, v1, s2
	s_addc_u32 s27, s31, s14
	s_add_i32 s34, s33, 0
	v_add_lshl_u32 v132, v0, v2, 1
	s_add_i32 m0, s34, 0x10000
	v_readlane_b32 s0, v253, 34
	global_load_lds_dwordx4 v132, s[26:27]
	s_add_i32 m0, s34, 0x12000
	v_readlane_b32 s1, v253, 35
	s_add_u32 s14, s28, s0
	s_addc_u32 s15, s29, s1
	s_add_u32 s0, s26, s10
	global_load_lds_dwordx4 v128, s[26:27]
	s_addc_u32 s1, s27, s11
	s_add_i32 m0, s34, 0x14000
	v_mov_b32_e32 v133, v177
	v_mov_b32_e32 v129, v177
	global_load_lds_dwordx4 v132, s[0:1]
	s_add_i32 m0, s34, 0x16000
	v_lshl_add_u64 v[4:5], s[0:1], 0, v[132:133]
	v_lshl_add_u64 v[6:7], s[0:1], 0, v[128:129]
	global_load_lds_dwordx4 v128, s[0:1]
	v_readlane_b32 s0, v253, 38
	v_readlane_b32 s1, v253, 39
	s_add_u32 s0, s14, s0
	v_lshlrev_b32_e32 v1, 11, v1
	s_addc_u32 s1, s15, s1
	s_add_i32 s35, s34, 0x2000
	v_lshl_add_u32 v134, v0, 1, v1
	s_mov_b32 m0, s34
	s_add_u32 s14, s0, 0x40000
	global_load_lds_dwordx4 v134, s[0:1]
	s_mov_b32 m0, s35
	s_addc_u32 s15, s1, 0
	s_add_i32 s36, s34, 0x4000
	global_load_lds_dwordx4 v130, s[0:1]
	s_mov_b32 m0, s36
	s_add_i32 s37, s34, 0x6000
	global_load_lds_dwordx4 v134, s[14:15]
	s_mov_b32 m0, s37
	v_mov_b32_e32 v135, v177
	global_load_lds_dwordx4 v130, s[14:15]
	v_mov_b32_e32 v131, v177
	s_cmp_eq_u32 s8, 1
	v_lshl_add_u64 v[0:1], s[26:27], 0, v[132:133]
	v_lshl_add_u64 v[2:3], s[26:27], 0, v[128:129]
	v_lshl_add_u64 v[8:9], s[0:1], 0, v[134:135]
	v_lshl_add_u64 v[10:11], s[0:1], 0, v[130:131]
	s_cselect_b64 s[14:15], -1, 0
	s_cmp_lg_u32 s8, 1
	s_cbranch_scc1 .LBB0_292
	s_barrier

.LBB0_313:
	s_mov_b64 s[0:1], 0x80000
	s_setprio 0
	s_getreg_b32 s6, hwreg(HW_REG_XCC_ID, 0, 4)
	s_waitcnt vmcnt(0)
	s_waitcnt vmcnt(0) lgkmcnt(0)
	s_barrier
	s_getreg_b32 s2, hwreg(HW_REG_HW_ID, 0, 6)
	s_and_b32 s2, s2, 63
	s_lshl_b32 s2, s2, 2
	s_add_i32 s2, s2, 0
	s_add_i32 s2, s2, 0x22ef0
	v_mov_b32_e32 v0, s2
	ds_read_b32 v0, v0
	s_waitcnt lgkmcnt(0)
	v_readfirstlane_b32 s2, v0
	v_mov_b32_e32 v0, v177
	s_nop 0
	v_mbcnt_lo_u32_b32 v0, -1, v0
	v_mbcnt_hi_u32_b32 v0, -1, v0
	v_lshl_add_u32 v0, s2, 6, v0
	s_nop 0
	v_cmp_eq_u32_e32 vcc, 0, v0
	s_and_saveexec_b64 s[2:3], vcc
	v_readlane_b32 s24, v254, 31
	s_xor_b64 s[2:3], exec, s[2:3]
	v_readlane_b32 s25, v254, 32
	s_mov_b32 s27, 1.0
	s_cbranch_execz .LBB0_366
	v_readlane_b32 s4, v254, 37
	s_waitcnt vmcnt(0) expcnt(0) lgkmcnt(0)
	s_nop 0
	v_mov_b32_e32 v0, s4
	ds_read_b32 v2, v0
	s_add_u32 s4, s66, s0
	v_readlane_b32 s0, v254, 38
	s_addc_u32 s5, s67, s1
	s_and_b32 s18, s6, 15
	v_mov_b32_e32 v0, s0
	ds_read_b32 v0, v0
	s_waitcnt lgkmcnt(1)
	v_cmp_ne_u32_e32 vcc, 0, v2
	s_cbranch_vccnz .LBB0_329
	s_add_u32 s0, s4, 0x1000
	s_addc_u32 s1, s5, 0
	s_add_u32 s6, s4, 0x1100
	s_addc_u32 s7, s5, 0
	s_add_u32 s8, s4, 0x1200
	s_addc_u32 s9, s5, 0
	s_add_u32 s10, s4, 0x1300
	s_addc_u32 s11, s5, 0
	s_mov_b32 s19, 1
	s_branch .LBB0_317

.LBB0_366:
	s_or_b64 exec, exec, s[2:3]
	s_mov_b64 s[6:7], 0xe800000
	s_mov_b64 s[8:9], 0x6100000
	s_mov_b64 s[4:5], 0xf000000
	s_mov_b32 s10, 17
	s_mov_b32 s0, 20
	s_waitcnt lgkmcnt(0)
	s_barrier
	s_getreg_b32 s100, hwreg(HW_REG_HW_ID, 0, 6)
	s_and_b32 s100, s100, 63
	s_lshl_b32 s100, s100, 2
	s_add_i32 s100, s100, 0x22ef0
	v_mov_b32_e32 v240, s100
	ds_read_b32 v240, v240
	s_waitcnt lgkmcnt(0)
	v_readfirstlane_b32 s100, v240
	s_nop 1
	s_cmp_ge_u32 s100, 4
	s_cbranch_scc0 .Lgp_4
	s_setprio 1
.Lgp_4:
	s_getreg_b32 s1, hwreg(HW_REG_HW_ID, 0, 6)
	s_and_b32 s1, s1, 63
	s_lshl_b32 s1, s1, 2
	s_add_i32 s1, s1, 0
	s_add_i32 s1, s1, 0x22ef0
	v_mov_b32_e32 v0, s1
	ds_read_b32 v0, v0
	v_readlane_b32 s12, v253, 10
	v_readlane_b32 s13, v253, 11
	s_movk_i32 s18, 0x1fff
	s_movk_i32 s2, 0x100
	s_waitcnt lgkmcnt(0)
	v_readfirstlane_b32 s1, v0
	v_mov_b32_e32 v0, v177
	s_and_b64 vcc, exec, s[12:13]
	v_mbcnt_lo_u32_b32 v0, -1, v0
	v_mbcnt_hi_u32_b32 v0, -1, v0
	v_lshl_add_u32 v12, s1, 6, v0
	s_nop 0
	v_readfirstlane_b32 s20, v12
	s_cbranch_vccz .LBB0_458
	v_lshlrev_b32_e32 v0, 4, v12
	v_add_u32_e32 v1, 0x2000, v0
	v_ashrrev_i32_e32 v2, 31, v1
	v_lshrrev_b32_e32 v2, 22, v2
	v_add_u32_e32 v2, v1, v2
	v_ashrrev_i32_e32 v13, 10, v2
	v_mul_i32_i24_e32 v3, 0x400, v13
	v_sub_u32_e32 v1, v1, v3
	v_lshrrev_b32_e32 v3, 4, v1
	v_bitop3_b32 v1, v3, v1, 32 bitop3:0x6c
	v_ashrrev_i32_e32 v3, 31, v1
	v_lshrrev_b32_e32 v3, 26, v3
	v_add_u32_e32 v3, v1, v3
	v_ashrrev_i32_e32 v14, 6, v3
	v_and_b32_e32 v3, 0xc0, v3
	v_sub_u32_e32 v1, v1, v3
	v_mov_b32_e32 v4, 1
	v_lshlrev_b32_e32 v2, 5, v13
	v_ashrrev_i16_sdwa v1, v4, sext(v1) dst_sel:DWORD dst_unused:UNUSED_PAD src0_sel:DWORD src1_sel:BYTE_0
	v_and_b32_e32 v2, 32, v2
	v_bfe_i32 v15, v1, 0, 16
	v_add_u32_e32 v1, v2, v15
	v_lshlrev_b32_e32 v2, 3, v13
	v_and_b32_e32 v2, -16, v2
	v_add_u32_e32 v2, v14, v2
	v_mul_lo_u32 v3, v2, s2
	v_lshlrev_b32_e32 v2, 9, v2
	v_lshl_add_u32 v146, v1, 1, v2
	v_bfe_i32 v2, v12, 27, 1
	s_add_u32 s30, s66, s6
	v_lshrrev_b32_e32 v2, 22, v2
	s_addc_u32 s31, s67, s7
	v_add_u32_e32 v2, v0, v2
	s_add_u32 s33, s66, s8
	v_and_b32_e32 v2, 0xfffffc00, v2
	s_addc_u32 s34, s67, s9
	s_ashr_i32 s11, s10, 31
	v_sub_u32_e32 v0, v0, v2
	s_lshl_b64 s[6:7], s[10:11], 3
	v_readlane_b32 s10, v253, 1
	v_lshrrev_b32_e32 v2, 4, v0
	v_readlane_b32 s11, v253, 2
	s_add_u32 s6, s10, s6
	v_bitop3_b32 v2, v2, v0, 32 bitop3:0x6c
	v_ashrrev_i32_e32 v0, 31, v0
	s_addc_u32 s7, s11, s7
	s_ashr_i32 s1, s0, 31
	v_lshrrev_b32_e32 v0, 26, v0
	s_lshl_b64 s[0:1], s[0:1], 3
	v_add_lshl_u32 v144, v1, v3, 1
	v_ashrrev_i32_e32 v1, 31, v12
	v_add_u32_e32 v0, v2, v0
	s_add_u32 s0, s10, s0
	v_lshrrev_b32_e32 v1, 26, v1
	v_ashrrev_i32_e32 v17, 6, v0
	s_addc_u32 s1, s11, s1
	s_ashr_i32 s3, s2, 31
	v_add_u32_e32 v1, v12, v1
	v_mul_i32_i24_e32 v0, 64, v17
	v_readlane_b32 s16, v253, 59
	s_lshl_b64 s[14:15], s[2:3], 9
	v_ashrrev_i32_e32 v16, 6, v1
	v_sub_u32_e32 v0, v2, v0
	v_readlane_b32 s17, v253, 60
	s_load_dwordx2 s[8:9], s[6:7], 0x0
	s_load_dwordx2 s[10:11], s[0:1], 0x0
	v_lshlrev_b32_e32 v1, 5, v16
	v_ashrrev_i16_sdwa v0, v4, sext(v0) dst_sel:DWORD dst_unused:UNUSED_PAD src0_sel:DWORD src1_sel:BYTE_0
	s_mul_i32 s0, s14, s17
	s_mul_hi_u32 s1, s14, s16
	v_and_b32_e32 v1, 32, v1
	v_bfe_i32 v18, v0, 0, 16
	s_add_i32 s6, s1, s0
	s_lshr_b64 s[0:1], s[2:3], 23
	s_ashr_i32 s19, s20, 6
	v_add_u32_e32 v0, v1, v18
	v_lshlrev_b32_e32 v1, 3, v16
	s_mul_i32 s0, s0, s16
	s_ashr_i32 s18, s20, 8
	s_lshl_b64 s[12:13], s[2:3], 8
	s_lshl_b32 s35, s19, 10
	v_and_b32_e32 v1, -16, v1
	s_add_i32 s6, s6, s0
	s_mul_i32 s0, s14, s16
	v_add_u32_e32 v1, v17, v1
	s_add_u32 s0, s33, s0
	v_mul_lo_u32 v2, v1, s2
	s_addc_u32 s1, s34, s6
	s_add_i32 s36, s35, 0
	v_add_lshl_u32 v148, v0, v2, 1
	s_add_i32 m0, s36, 0x10000
	v_mov_b32_e32 v149, v177
	global_load_lds_dwordx4 v148, s[0:1]
	s_add_i32 m0, s36, 0x12000
	s_add_u32 s6, s0, s12
	global_load_lds_dwordx4 v144, s[0:1]
	s_addc_u32 s7, s1, s13
	s_add_i32 m0, s36, 0x14000
	v_mov_b32_e32 v145, v177
	global_load_lds_dwordx4 v148, s[6:7]
	s_add_i32 m0, s36, 0x16000
	v_lshl_add_u64 v[4:5], s[6:7], 0, v[148:149]
	v_lshl_add_u64 v[6:7], s[6:7], 0, v[144:145]
	global_load_lds_dwordx4 v144, s[6:7]
	v_readlane_b32 s6, v254, 9
	v_readlane_b32 s7, v254, 10
	s_add_u32 s6, s30, s6
	v_lshlrev_b32_e32 v1, 9, v1
	s_addc_u32 s7, s31, s7
	s_add_i32 s37, s36, 0x2000
	v_lshl_add_u32 v150, v0, 1, v1
	s_mov_b32 m0, s36
	s_add_u32 s16, s6, 0x10000
	global_load_lds_dwordx4 v150, s[6:7]
	s_mov_b32 m0, s37
	s_addc_u32 s17, s7, 0
	s_add_i32 s40, s36, 0x4000
	global_load_lds_dwordx4 v146, s[6:7]
	s_mov_b32 m0, s40
	s_add_i32 s41, s36, 0x6000
	global_load_lds_dwordx4 v150, s[16:17]
	s_mov_b32 m0, s41
	v_mov_b32_e32 v151, v177
	global_load_lds_dwordx4 v146, s[16:17]
	v_mov_b32_e32 v147, v177
	s_cmp_eq_u32 s18, 1
	v_lshl_add_u64 v[0:1], s[0:1], 0, v[148:149]
	v_lshl_add_u64 v[2:3], s[0:1], 0, v[144:145]
	v_lshl_add_u64 v[8:9], s[6:7], 0, v[150:151]
	v_lshl_add_u64 v[10:11], s[6:7], 0, v[146:147]
	s_cselect_b64 s[16:17], -1, 0
	s_cmp_lg_u32 s18, 1
	s_cbranch_scc1 .LBB0_369
	s_barrier

.LBB0_458:
	s_mov_b64 s[0:1], 0x80000
	s_setprio 0
	s_getreg_b32 s6, hwreg(HW_REG_XCC_ID, 0, 4)
	s_waitcnt vmcnt(0)
	s_waitcnt vmcnt(0)
	s_barrier
	s_getreg_b32 s2, hwreg(HW_REG_HW_ID, 0, 6)
	s_and_b32 s2, s2, 63
	s_lshl_b32 s2, s2, 2
	s_add_i32 s2, s2, 0
	s_add_i32 s2, s2, 0x22ef0
	v_mov_b32_e32 v0, s2
	ds_read_b32 v0, v0
	s_waitcnt lgkmcnt(0)
	v_readfirstlane_b32 s2, v0
	v_mov_b32_e32 v0, v177
	s_nop 0
	v_mbcnt_lo_u32_b32 v0, -1, v0
	v_mbcnt_hi_u32_b32 v0, -1, v0
	v_lshl_add_u32 v0, s2, 6, v0
	s_nop 0
	v_cmp_eq_u32_e32 vcc, 0, v0
	s_and_saveexec_b64 s[2:3], vcc
	s_xor_b64 s[2:3], exec, s[2:3]
	s_cbranch_execz .LBB0_511
	v_readlane_b32 s4, v254, 37
	s_waitcnt vmcnt(0) expcnt(0) lgkmcnt(0)
	s_nop 0
	v_mov_b32_e32 v0, s4
	ds_read_b32 v2, v0
	s_add_u32 s4, s66, s0
	v_readlane_b32 s0, v254, 38
	s_addc_u32 s5, s67, s1
	s_and_b32 s18, s6, 15
	v_mov_b32_e32 v0, s0
	ds_read_b32 v0, v0
	s_waitcnt lgkmcnt(1)
	v_cmp_ne_u32_e32 vcc, 0, v2
	s_cbranch_vccnz .LBB0_474
	s_add_u32 s0, s4, 0x1000
	s_addc_u32 s1, s5, 0
	s_add_u32 s6, s4, 0x1100
	s_addc_u32 s7, s5, 0
	s_add_u32 s8, s4, 0x1200
	s_addc_u32 s9, s5, 0
	s_add_u32 s10, s4, 0x1300
	s_addc_u32 s11, s5, 0
	s_mov_b32 s19, 1
	s_branch .LBB0_462

.Lgp_9:
.LBB0_854:
	s_cbranch_execnz .LBB0_1370

.LBB0_979:
	s_mov_b64 s[0:1], 0x80000
	s_setprio 0
	s_getreg_b32 s6, hwreg(HW_REG_XCC_ID, 0, 4)
	s_waitcnt vmcnt(0)
	s_waitcnt vmcnt(0) lgkmcnt(0)
	s_barrier
	s_getreg_b32 s2, hwreg(HW_REG_HW_ID, 0, 6)
	s_and_b32 s2, s2, 63
	s_lshl_b32 s2, s2, 2
	s_add_i32 s2, s2, 0
	s_add_i32 s2, s2, 0x22ef0
	v_mov_b32_e32 v0, s2
	ds_read_b32 v0, v0
	s_waitcnt lgkmcnt(0)
	v_readfirstlane_b32 s2, v0
	v_mov_b32_e32 v0, v177
	s_nop 0
	v_mbcnt_lo_u32_b32 v0, -1, v0
	v_mbcnt_hi_u32_b32 v0, -1, v0
	v_lshl_add_u32 v0, s2, 6, v0
	s_nop 0
	v_cmp_eq_u32_e32 vcc, 0, v0
	s_and_saveexec_b64 s[2:3], vcc
	s_xor_b64 s[2:3], exec, s[2:3]
	s_movk_i32 s25, 0x1000
	s_cbranch_execz .LBB0_1032
	v_readlane_b32 s4, v254, 37
	s_waitcnt vmcnt(0) expcnt(0) lgkmcnt(0)
	s_nop 0
	v_mov_b32_e32 v0, s4
	ds_read_b32 v2, v0
	s_add_u32 s4, s66, s0
	v_readlane_b32 s0, v254, 38
	s_addc_u32 s5, s67, s1
	s_and_b32 s18, s6, 15
	v_mov_b32_e32 v0, s0
	ds_read_b32 v0, v0
	s_waitcnt lgkmcnt(1)
	v_cmp_ne_u32_e32 vcc, 0, v2
	s_cbranch_vccnz .LBB0_995
	s_add_u32 s0, s4, 0x1000
	s_addc_u32 s1, s5, 0
	s_add_u32 s6, s4, 0x1100
	s_addc_u32 s7, s5, 0
	s_add_u32 s8, s4, 0x1200
	s_addc_u32 s9, s5, 0
	s_add_u32 s10, s4, 0x1300
	s_addc_u32 s11, s5, 0
	s_mov_b32 s19, 1
	s_branch .LBB0_983

.LBB0_1032:
	s_or_b64 exec, exec, s[2:3]
	v_readlane_b32 s2, v254, 61
	v_readlane_b32 s3, v254, 62
	s_and_b64 s[2:3], s[2:3], exec
	s_mov_b32 s2, 0x1100000
	s_cselect_b32 s48, s2, 0x1000000
	s_mov_b64 s[0:1], 0xa800000
	s_mov_b64 s[4:5], s[48:49]
	s_mov_b64 s[2:3], 0x10800000
	s_waitcnt lgkmcnt(0)
	s_barrier
	s_getreg_b32 s100, hwreg(HW_REG_HW_ID, 0, 6)
	s_and_b32 s100, s100, 63
	s_lshl_b32 s100, s100, 2
	s_add_i32 s100, s100, 0x22ef0
	v_mov_b32_e32 v240, s100
	ds_read_b32 v240, v240
	s_waitcnt lgkmcnt(0)
	v_readfirstlane_b32 s100, v240
	s_nop 1
	s_cmp_ge_u32 s100, 4
	s_cbranch_scc0 .Lgp_10
	s_setprio 1
.Lgp_10:
	s_getreg_b32 s6, hwreg(HW_REG_HW_ID, 0, 6)
	s_and_b32 s6, s6, 63
	s_lshl_b32 s6, s6, 2
	s_add_i32 s6, s6, 0
	s_add_i32 s6, s6, 0x22ef0
	v_mov_b32_e32 v0, s6
	ds_read_b32 v0, v0
	v_readlane_b32 s10, v253, 25
	v_readlane_b32 s11, v253, 26
	s_movk_i32 s18, 0x1ff
	s_andn2_b64 vcc, exec, s[10:11]
	s_waitcnt lgkmcnt(0)
	v_readfirstlane_b32 s6, v0
	v_mov_b32_e32 v0, v177
	s_nop 0
	v_mbcnt_lo_u32_b32 v0, -1, v0
	v_mbcnt_hi_u32_b32 v0, -1, v0
	v_lshl_add_u32 v9, s6, 6, v0
	s_movk_i32 s6, 0x100
	v_readfirstlane_b32 s8, v9
	s_cbranch_vccnz .LBB0_1055
	v_lshlrev_b32_e32 v0, 4, v9
	v_add_u32_e32 v1, 0x2000, v0
	v_ashrrev_i32_e32 v2, 31, v1
	v_lshrrev_b32_e32 v2, 22, v2
	v_add_u32_e32 v2, v1, v2
	v_ashrrev_i32_e32 v8, 10, v2
	v_mul_i32_i24_e32 v3, 0x400, v8
	v_sub_u32_e32 v1, v1, v3
	v_lshrrev_b32_e32 v3, 4, v1
	v_bitop3_b32 v1, v3, v1, 32 bitop3:0x6c
	v_ashrrev_i32_e32 v3, 31, v1
	v_lshrrev_b32_e32 v3, 26, v3
	v_add_u32_e32 v3, v1, v3
	v_ashrrev_i32_e32 v10, 6, v3
	v_and_b32_e32 v3, 0xc0, v3
	v_sub_u32_e32 v1, v1, v3
	v_mov_b32_e32 v4, 1
	v_lshlrev_b32_e32 v2, 5, v8
	v_ashrrev_i16_sdwa v1, v4, sext(v1) dst_sel:DWORD dst_unused:UNUSED_PAD src0_sel:DWORD src1_sel:BYTE_0
	v_and_b32_e32 v2, 32, v2
	v_bfe_i32 v11, v1, 0, 16
	v_add_u32_e32 v1, v2, v11
	v_lshlrev_b32_e32 v2, 3, v8
	v_and_b32_e32 v2, -16, v2
	v_add_u32_e32 v2, v10, v2
	v_lshlrev_b32_e32 v3, 12, v2
	v_lshl_add_u32 v128, v1, 1, v3
	v_lshlrev_b32_e32 v1, 11, v2
	v_bfe_i32 v2, v9, 27, 1
	v_lshrrev_b32_e32 v2, 22, v2
	v_add_u32_e32 v2, v0, v2
	v_and_b32_e32 v2, 0xfffffc00, v2
	v_sub_u32_e32 v0, v0, v2
	v_lshrrev_b32_e32 v2, 4, v0
	v_bitop3_b32 v2, v2, v0, 32 bitop3:0x6c
	v_ashrrev_i32_e32 v0, 31, v0
	v_lshrrev_b32_e32 v0, 26, v0
	v_sub_u32_e32 v130, v128, v1
	v_ashrrev_i32_e32 v1, 31, v9
	v_add_u32_e32 v0, v2, v0
	v_lshrrev_b32_e32 v1, 26, v1
	v_ashrrev_i32_e32 v13, 6, v0
	v_add_u32_e32 v1, v9, v1
	v_mul_i32_i24_e32 v0, 64, v13
	s_add_u32 s24, s66, s0
	v_ashrrev_i32_e32 v12, 6, v1
	v_sub_u32_e32 v0, v2, v0
	s_addc_u32 s25, s67, s1
	v_lshlrev_b32_e32 v1, 5, v12
	v_ashrrev_i16_sdwa v0, v4, sext(v0) dst_sel:DWORD dst_unused:UNUSED_PAD src0_sel:DWORD src1_sel:BYTE_0
	s_add_u32 s26, s66, s4
	v_and_b32_e32 v1, 32, v1
	v_bfe_i32 v14, v0, 0, 16
	s_addc_u32 s27, s67, s5
	s_ashr_i32 s10, s8, 6
	v_add_u32_e32 v0, v1, v14
	v_lshlrev_b32_e32 v1, 3, v12
	s_ashr_i32 s7, s8, 8
	s_lshl_b32 s28, s10, 10
	v_and_b32_e32 v1, -16, v1
	v_readlane_b32 s12, v253, 49
	v_add_u32_e32 v1, v13, v1
	v_readlane_b32 s13, v253, 50
	s_add_u32 s0, s26, s12
	v_lshlrev_b32_e32 v2, 12, v1
	s_addc_u32 s1, s27, s13
	s_add_i32 s29, s28, 0
	v_lshl_add_u32 v176, v0, 1, v2
	s_add_i32 m0, s29, 0x10000
	v_readlane_b32 s4, v253, 47
	global_load_lds_dwordx4 v176, s[0:1]
	s_add_i32 m0, s29, 0x12000
	v_readlane_b32 s5, v253, 48
	s_add_u32 s9, s24, s4
	s_addc_u32 s11, s25, s5
	s_add_u32 s4, s0, 0x80000
	global_load_lds_dwordx4 v128, s[0:1]
	s_addc_u32 s5, s1, 0
	s_add_i32 m0, s29, 0x14000
	v_lshlrev_b32_e32 v0, 11, v1
	global_load_lds_dwordx4 v176, s[4:5]
	s_add_i32 m0, s29, 0x16000
	s_add_u32 s20, s9, s12
	s_addc_u32 s21, s11, s13
	s_add_i32 s30, s29, 0x2000
	v_sub_u32_e32 v132, v176, v0
	global_load_lds_dwordx4 v128, s[4:5]
	s_mov_b32 m0, s29
	s_add_u32 s4, s20, 0x40000
	global_load_lds_dwordx4 v132, s[20:21]
	s_mov_b32 m0, s30
	s_addc_u32 s5, s21, 0
	s_add_i32 s31, s29, 0x4000
	global_load_lds_dwordx4 v130, s[20:21]
	s_mov_b32 m0, s31
	s_add_i32 s33, s29, 0x6000
	global_load_lds_dwordx4 v132, s[4:5]
	s_mov_b32 m0, s33
	v_mov_b32_e32 v129, v177
	global_load_lds_dwordx4 v130, s[4:5]
	v_mov_b32_e32 v133, v177
	v_mov_b32_e32 v131, v177
	s_cmp_eq_u32 s7, 1
	v_lshl_add_u64 v[6:7], s[0:1], 0, v[176:177]
	v_lshl_add_u64 v[4:5], s[0:1], 0, v[128:129]
	v_lshl_add_u64 v[0:1], s[20:21], 0, v[132:133]
	s_cselect_b64 s[4:5], -1, 0
	s_cmp_lg_u32 s7, 1
	v_lshl_add_u64 v[2:3], s[20:21], 0, v[130:131]
	s_cbranch_scc1 .LBB0_1035
	s_barrier

.LBB0_1055:
	s_mov_b64 s[0:1], 0x80000
	s_setprio 0
	s_getreg_b32 s6, hwreg(HW_REG_XCC_ID, 0, 4)
	s_waitcnt vmcnt(0)
	s_waitcnt vmcnt(0) lgkmcnt(0)
	s_barrier
	s_getreg_b32 s2, hwreg(HW_REG_HW_ID, 0, 6)
	s_and_b32 s2, s2, 63
	s_lshl_b32 s2, s2, 2
	s_add_i32 s2, s2, 0
	s_add_i32 s2, s2, 0x22ef0
	v_mov_b32_e32 v0, s2
	ds_read_b32 v0, v0
	s_waitcnt lgkmcnt(0)
	v_readfirstlane_b32 s2, v0
	v_mov_b32_e32 v0, v177
	s_nop 0
	v_mbcnt_lo_u32_b32 v0, -1, v0
	v_mbcnt_hi_u32_b32 v0, -1, v0
	v_lshl_add_u32 v0, s2, 6, v0
	s_nop 0
	v_cmp_eq_u32_e32 vcc, 0, v0
	s_and_saveexec_b64 s[2:3], vcc
	s_cbranch_execz .LBB0_1107
	v_readlane_b32 s4, v254, 37
	s_waitcnt vmcnt(0) expcnt(0) lgkmcnt(0)
	s_nop 0
	v_mov_b32_e32 v0, s4
	ds_read_b32 v2, v0
	s_add_u32 s4, s66, s0
	v_readlane_b32 s0, v254, 38
	s_addc_u32 s5, s67, s1
	s_and_b32 s18, s6, 15
	v_mov_b32_e32 v0, s0
	ds_read_b32 v0, v0
	s_waitcnt lgkmcnt(1)
	v_cmp_ne_u32_e32 vcc, 0, v2
	s_cbranch_vccnz .LBB0_1071
	s_add_u32 s0, s4, 0x1000
	s_addc_u32 s1, s5, 0
	s_add_u32 s6, s4, 0x1100
	s_addc_u32 s7, s5, 0
	s_add_u32 s8, s4, 0x1200
	s_addc_u32 s9, s5, 0
	s_add_u32 s10, s4, 0x1300
	s_addc_u32 s11, s5, 0
	s_mov_b32 s19, 1
	s_branch .LBB0_1059

.Lgp_13:
.LBB0_1370:
	v_readlane_b32 s0, v254, 53
	v_readlane_b32 s1, v254, 54
	s_andn2_b64 vcc, exec, s[0:1]
	s_mov_b64 s[8:9], s[38:39]
	s_cbranch_vccnz .LBB0_1372
	s_mov_b32 s0, s49
	s_ashr_i32 s1, s0, 31
	s_lshl_b64 s[0:1], s[0:1], 3
	v_readlane_b32 s2, v253, 1
	v_readlane_b32 s3, v253, 2
	s_add_u32 s0, s2, s0
	s_addc_u32 s1, s3, s1
	s_load_dwordx2 s[8:9], s[0:1], 0x0

.LBB0_1414:
	s_mov_b64 s[2:3], 0x80000
	s_setprio 0
	s_getreg_b32 s8, hwreg(HW_REG_XCC_ID, 0, 4)
	s_waitcnt vmcnt(0)
	s_waitcnt lgkmcnt(0)
	s_barrier
	s_getreg_b32 s0, hwreg(HW_REG_HW_ID, 0, 6)
	s_and_b32 s0, s0, 63
	s_lshl_b32 s0, s0, 2
	s_add_i32 s0, s0, 0
	s_add_i32 s0, s0, 0x22ef0
	v_mov_b32_e32 v0, s0
	ds_read_b32 v0, v0
	s_waitcnt lgkmcnt(0)
	v_readfirstlane_b32 s0, v0
	v_mov_b32_e32 v0, v177
	s_nop 0
	v_mbcnt_lo_u32_b32 v0, -1, v0
	v_mbcnt_hi_u32_b32 v0, -1, v0
	v_lshl_add_u32 v0, s0, 6, v0
	s_nop 0
	v_cmp_eq_u32_e32 vcc, 0, v0
	s_and_saveexec_b64 s[4:5], vcc
	s_mov_b32 s18, 0x800000
	s_cbranch_execz .LBB0_1468
	v_readlane_b32 s0, v254, 37
	s_waitcnt vmcnt(0) expcnt(0) lgkmcnt(0)
	s_add_u32 s6, s66, s2
	v_mov_b32_e32 v0, s0
	ds_read_b32 v2, v0
	v_readlane_b32 s0, v254, 38
	s_addc_u32 s7, s67, s3
	s_and_b32 s20, s8, 15
	v_mov_b32_e32 v0, s0
	ds_read_b32 v0, v0
	s_waitcnt lgkmcnt(1)
	v_cmp_ne_u32_e32 vcc, 0, v2
	s_cbranch_vccnz .LBB0_1432
	s_add_u32 s2, s6, 0x1000
	s_addc_u32 s3, s7, 0
	s_add_u32 s8, s6, 0x1100
	s_addc_u32 s9, s7, 0
	s_add_u32 s10, s6, 0x1200
	s_addc_u32 s11, s7, 0
	s_add_u32 s12, s6, 0x1300
	s_addc_u32 s13, s7, 0
	s_mov_b32 s21, 1
	s_branch .LBB0_1419

.LBB0_1526:
	s_or_b64 exec, exec, s[4:5]
	s_mul_i32 s1, s26, 0xb00000
	s_mul_hi_u32 s0, s26, 0xb00000
	s_add_u32 s8, s1, 0x1200000
	s_mov_b64 s[2:3], 0x6500800
	s_addc_u32 s9, s0, 0
	s_mov_b64 s[6:7], 0x8800000
	s_waitcnt lgkmcnt(0)
	s_barrier
	s_getreg_b32 s100, hwreg(HW_REG_HW_ID, 0, 6)
	s_and_b32 s100, s100, 63
	s_lshl_b32 s100, s100, 2
	s_add_i32 s100, s100, 0x22ef0
	v_mov_b32_e32 v240, s100
	ds_read_b32 v240, v240
	s_waitcnt lgkmcnt(0)
	v_readfirstlane_b32 s100, v240
	s_nop 1
	s_cmp_ge_u32 s100, 4
	s_cbranch_scc0 .Lgp_15
	s_setprio 1
.Lgp_15:
	s_getreg_b32 s0, hwreg(HW_REG_HW_ID, 0, 6)
	s_and_b32 s0, s0, 63
	s_lshl_b32 s0, s0, 2
	s_add_i32 s0, s0, 0
	s_add_i32 s0, s0, 0x22ef0
	v_mov_b32_e32 v0, s0
	ds_read_b32 v0, v0
	s_movk_i32 s4, 0x400
	s_waitcnt lgkmcnt(0)
	v_readfirstlane_b32 s0, v0
	v_mov_b32_e32 v0, v177
	s_nop 0
	v_mbcnt_lo_u32_b32 v0, -1, v0
	v_mbcnt_hi_u32_b32 v0, -1, v0
	v_lshl_add_u32 v12, s0, 6, v0
	v_readlane_b32 s0, v253, 31
	v_readlane_b32 s1, v253, 32
	s_andn2_b64 vcc, exec, s[0:1]
	v_readfirstlane_b32 s16, v12
	s_cbranch_vccnz .LBB0_1545
	v_lshlrev_b32_e32 v0, 4, v12
	v_add_u32_e32 v1, 0x2000, v0
	v_ashrrev_i32_e32 v2, 31, v1
	v_lshrrev_b32_e32 v2, 22, v2
	v_add_u32_e32 v2, v1, v2
	v_ashrrev_i32_e32 v13, 10, v2
	v_mul_i32_i24_e32 v3, 0x400, v13
	v_sub_u32_e32 v1, v1, v3
	v_lshrrev_b32_e32 v3, 4, v1
	v_bitop3_b32 v1, v3, v1, 32 bitop3:0x6c
	v_ashrrev_i32_e32 v3, 31, v1
	v_lshrrev_b32_e32 v3, 26, v3
	v_add_u32_e32 v3, v1, v3
	v_ashrrev_i32_e32 v14, 6, v3
	v_and_b32_e32 v3, 0xc0, v3
	v_sub_u32_e32 v1, v1, v3
	v_mov_b32_e32 v4, 1
	v_lshlrev_b32_e32 v2, 5, v13
	v_ashrrev_i16_sdwa v1, v4, sext(v1) dst_sel:DWORD dst_unused:UNUSED_PAD src0_sel:DWORD src1_sel:BYTE_0
	v_and_b32_e32 v2, 32, v2
	v_bfe_i32 v15, v1, 0, 16
	v_add_u32_e32 v1, v2, v15
	v_lshlrev_b32_e32 v2, 3, v13
	v_and_b32_e32 v2, -16, v2
	v_add_u32_e32 v2, v14, v2
	v_mul_lo_u32 v3, v2, s4
	v_lshlrev_b32_e32 v2, 11, v2
	v_lshl_add_u32 v130, v1, 1, v2
	v_bfe_i32 v2, v12, 27, 1
	v_lshrrev_b32_e32 v2, 22, v2
	v_add_u32_e32 v2, v0, v2
	v_and_b32_e32 v2, 0xfffffc00, v2
	v_sub_u32_e32 v0, v0, v2
	v_lshrrev_b32_e32 v2, 4, v0
	v_bitop3_b32 v2, v2, v0, 32 bitop3:0x6c
	v_ashrrev_i32_e32 v0, 31, v0
	v_lshrrev_b32_e32 v0, 26, v0
	s_add_u32 s26, s66, s2
	v_add_lshl_u32 v128, v1, v3, 1
	v_ashrrev_i32_e32 v1, 31, v12
	v_add_u32_e32 v0, v2, v0
	s_addc_u32 s27, s67, s3
	v_lshrrev_b32_e32 v1, 26, v1
	v_ashrrev_i32_e32 v17, 6, v0
	s_add_u32 s28, s66, s8
	v_add_u32_e32 v1, v12, v1
	v_mul_i32_i24_e32 v0, 64, v17
	s_addc_u32 s29, s67, s9
	s_ashr_i32 s5, s4, 31
	v_ashrrev_i32_e32 v16, 6, v1
	v_sub_u32_e32 v0, v2, v0
	v_readlane_b32 s12, v253, 55
	s_lshl_b64 s[10:11], s[4:5], 9
	v_lshlrev_b32_e32 v1, 5, v16
	v_ashrrev_i16_sdwa v0, v4, sext(v0) dst_sel:DWORD dst_unused:UNUSED_PAD src0_sel:DWORD src1_sel:BYTE_0
	v_readlane_b32 s13, v253, 56
	v_and_b32_e32 v1, 32, v1
	v_bfe_i32 v18, v0, 0, 16
	s_mul_i32 s0, s10, s13
	s_mul_hi_u32 s1, s10, s12
	s_lshr_b64 s[2:3], s[4:5], 23
	s_ashr_i32 s15, s16, 6
	v_add_u32_e32 v0, v1, v18
	v_lshlrev_b32_e32 v1, 3, v16
	s_add_i32 s0, s1, s0
	s_mul_i32 s1, s2, s12
	s_ashr_i32 s14, s16, 8
	s_lshl_b64 s[8:9], s[4:5], 8
	s_lshl_b32 s30, s15, 10
	v_and_b32_e32 v1, -16, v1
	s_add_i32 s0, s0, s1
	s_mul_i32 s1, s10, s12
	v_add_u32_e32 v1, v17, v1
	s_add_u32 s24, s28, s1
	v_mul_lo_u32 v2, v1, s4
	s_addc_u32 s25, s29, s0
	s_add_i32 s31, s30, 0
	v_add_lshl_u32 v176, v0, v2, 1
	s_add_i32 m0, s31, 0x10000
	v_readlane_b32 s0, v254, 5
	global_load_lds_dwordx4 v176, s[24:25]
	s_add_i32 m0, s31, 0x12000
	v_readlane_b32 s1, v254, 6
	s_add_u32 s0, s26, s0
	s_addc_u32 s1, s27, s1
	s_add_u32 s2, s24, s8
	global_load_lds_dwordx4 v128, s[24:25]
	s_addc_u32 s3, s25, s9
	s_add_i32 m0, s31, 0x14000
	v_mov_b32_e32 v129, v177
	global_load_lds_dwordx4 v176, s[2:3]
	s_add_i32 m0, s31, 0x16000
	v_lshl_add_u64 v[4:5], s[2:3], 0, v[176:177]
	v_lshl_add_u64 v[6:7], s[2:3], 0, v[128:129]
	global_load_lds_dwordx4 v128, s[2:3]
	v_readlane_b32 s2, v253, 53
	v_readlane_b32 s3, v253, 54
	s_add_u32 s2, s0, s2
	v_lshlrev_b32_e32 v1, 11, v1
	s_addc_u32 s3, s1, s3
	s_add_i32 s33, s31, 0x2000
	v_lshl_add_u32 v132, v0, 1, v1
	s_mov_b32 m0, s31
	s_add_u32 s12, s2, 0x40000
	global_load_lds_dwordx4 v132, s[2:3]
	s_mov_b32 m0, s33
	s_addc_u32 s13, s3, 0
	s_add_i32 s34, s31, 0x4000
	global_load_lds_dwordx4 v130, s[2:3]
	s_mov_b32 m0, s34
	s_add_i32 s35, s31, 0x6000
	global_load_lds_dwordx4 v132, s[12:13]
	s_mov_b32 m0, s35
	v_mov_b32_e32 v133, v177
	global_load_lds_dwordx4 v130, s[12:13]
	v_mov_b32_e32 v131, v177
	s_cmp_eq_u32 s14, 1
	v_lshl_add_u64 v[0:1], s[24:25], 0, v[176:177]
	v_lshl_add_u64 v[2:3], s[24:25], 0, v[128:129]
	v_lshl_add_u64 v[8:9], s[2:3], 0, v[132:133]
	v_lshl_add_u64 v[10:11], s[2:3], 0, v[130:131]
	s_cselect_b64 s[12:13], -1, 0
	s_cmp_lg_u32 s14, 1
	s_cbranch_scc1 .LBB0_1529
	s_barrier

.LBB0_1545:
	s_mov_b64 s[2:3], 0x80000
	s_setprio 0
	s_getreg_b32 s8, hwreg(HW_REG_XCC_ID, 0, 4)
	s_waitcnt vmcnt(0)
	s_waitcnt vmcnt(0) lgkmcnt(0)
	s_barrier
	s_getreg_b32 s0, hwreg(HW_REG_HW_ID, 0, 6)
	s_and_b32 s0, s0, 63
	s_lshl_b32 s0, s0, 2
	s_add_i32 s0, s0, 0
	s_add_i32 s0, s0, 0x22ef0
	v_mov_b32_e32 v0, s0
	ds_read_b32 v0, v0
	s_waitcnt lgkmcnt(0)
	v_readfirstlane_b32 s0, v0
	v_mov_b32_e32 v0, v177
	s_nop 0
	v_mbcnt_lo_u32_b32 v0, -1, v0
	v_mbcnt_hi_u32_b32 v0, -1, v0
	v_lshl_add_u32 v0, s0, 6, v0
	s_nop 0
	v_cmp_eq_u32_e32 vcc, 0, v0
	s_and_saveexec_b64 s[4:5], vcc
	s_cbranch_execz .LBB0_1598
	v_readlane_b32 s0, v254, 37
	s_waitcnt vmcnt(0) expcnt(0) lgkmcnt(0)
	s_add_u32 s6, s66, s2
	v_mov_b32_e32 v0, s0
	ds_read_b32 v2, v0
	v_readlane_b32 s0, v254, 38
	s_addc_u32 s7, s67, s3
	s_and_b32 s20, s8, 15
	v_mov_b32_e32 v0, s0
	ds_read_b32 v0, v0
	s_waitcnt lgkmcnt(1)
	v_cmp_ne_u32_e32 vcc, 0, v2
	s_cbranch_vccnz .LBB0_1562
	s_add_u32 s2, s6, 0x1000
	s_addc_u32 s3, s7, 0
	s_add_u32 s8, s6, 0x1100
	s_addc_u32 s9, s7, 0
	s_add_u32 s10, s6, 0x1200
	s_addc_u32 s11, s7, 0
	s_add_u32 s12, s6, 0x1300
	s_addc_u32 s13, s7, 0
	s_mov_b32 s21, 1
	s_branch .LBB0_1550

.LBB0_1598:
	s_or_b64 exec, exec, s[4:5]
	s_mul_i32 s1, s26, 0x580000
	s_mul_hi_u32 s0, s26, 0x580000
	s_add_u32 s6, s1, 0x3e00000
	s_mov_b64 s[4:5], 0x8800000
	s_addc_u32 s7, s0, 0
	s_waitcnt lgkmcnt(0)
	s_barrier
	s_getreg_b32 s100, hwreg(HW_REG_HW_ID, 0, 6)
	s_and_b32 s100, s100, 63
	s_lshl_b32 s100, s100, 2
	s_add_i32 s100, s100, 0x22ef0
	v_mov_b32_e32 v240, s100
	ds_read_b32 v240, v240
	s_waitcnt lgkmcnt(0)
	v_readfirstlane_b32 s100, v240
	s_nop 1
	s_cmp_ge_u32 s100, 4
	s_cbranch_scc0 .Lgp_16
	s_setprio 1
.Lgp_16:
	s_getreg_b32 s0, hwreg(HW_REG_HW_ID, 0, 6)
	s_and_b32 s0, s0, 63
	s_lshl_b32 s0, s0, 2
	s_add_i32 s0, s0, 0
	s_add_i32 s0, s0, 0x22ef0
	v_mov_b32_e32 v0, s0
	ds_read_b32 v0, v0
	s_movk_i32 s2, 0xb00
	s_and_b64 vcc, exec, s[58:59]
	s_waitcnt lgkmcnt(0)
	v_readfirstlane_b32 s0, v0
	v_mov_b32_e32 v0, v177
	s_nop 0
	v_mbcnt_lo_u32_b32 v0, -1, v0
	v_mbcnt_hi_u32_b32 v0, -1, v0
	v_lshl_add_u32 v12, s0, 6, v0
	s_nop 0
	v_readfirstlane_b32 s14, v12
	s_cbranch_vccnz .LBB0_1623
	v_lshlrev_b32_e32 v0, 4, v12
	v_add_u32_e32 v1, 0x2000, v0
	v_ashrrev_i32_e32 v2, 31, v1
	v_lshrrev_b32_e32 v2, 22, v2
	v_add_u32_e32 v2, v1, v2
	v_ashrrev_i32_e32 v14, 10, v2
	v_lshlrev_b32_e32 v2, 5, v14
	v_and_b32_e32 v13, 32, v2
	v_mul_i32_i24_e32 v2, 0x400, v14
	v_sub_u32_e32 v1, v1, v2
	v_lshrrev_b32_e32 v2, 4, v1
	v_bitop3_b32 v1, v2, v1, 32 bitop3:0x6c
	v_ashrrev_i32_e32 v2, 31, v1
	v_lshrrev_b32_e32 v2, 26, v2
	v_add_u32_e32 v2, v1, v2
	v_ashrrev_i32_e32 v16, 6, v2
	v_and_b32_e32 v2, 0xc0, v2
	v_sub_u32_e32 v1, v1, v2
	v_mov_b32_e32 v4, 1
	v_lshlrev_b32_e32 v2, 3, v14
	v_ashrrev_i16_sdwa v1, v4, sext(v1) dst_sel:DWORD dst_unused:UNUSED_PAD src0_sel:DWORD src1_sel:BYTE_0
	v_and_b32_e32 v2, -16, v2
	s_add_u32 s22, s66, s4
	v_bfe_i32 v15, v1, 0, 16
	v_add_u32_e32 v2, v16, v2
	s_movk_i32 s4, 0xb00
	v_add_u32_e32 v1, v13, v15
	v_mul_lo_u32 v3, v2, s2
	v_mul_lo_u32 v2, v2, s4
	v_add_lshl_u32 v144, v1, v3, 1
	v_add_lshl_u32 v146, v1, v2, 1
	v_ashrrev_i32_e32 v1, 31, v12
	v_lshrrev_b32_e32 v1, 26, v1
	v_add_u32_e32 v1, v12, v1
	v_ashrrev_i32_e32 v18, 6, v1
	v_lshlrev_b32_e32 v1, 5, v18
	v_and_b32_e32 v17, 32, v1
	v_bfe_i32 v1, v12, 27, 1
	v_lshrrev_b32_e32 v1, 22, v1
	v_add_u32_e32 v1, v0, v1
	v_and_b32_e32 v1, 0xfffffc00, v1
	v_sub_u32_e32 v0, v0, v1
	v_lshrrev_b32_e32 v1, 4, v0
	v_bitop3_b32 v1, v1, v0, 32 bitop3:0x6c
	v_ashrrev_i32_e32 v0, 31, v0
	v_lshrrev_b32_e32 v0, 26, v0
	v_add_u32_e32 v0, v1, v0
	v_ashrrev_i32_e32 v20, 6, v0
	s_addc_u32 s23, s67, s5
	v_mul_i32_i24_e32 v0, 64, v20
	s_add_u32 s24, s66, s6
	v_sub_u32_e32 v0, v1, v0
	v_lshlrev_b32_e32 v1, 3, v18
	s_addc_u32 s25, s67, s7
	s_ashr_i32 s3, s2, 31
	v_and_b32_e32 v1, -16, v1
	v_readlane_b32 s12, v253, 57
	s_lshl_b64 s[8:9], s[2:3], 9
	v_add_u32_e32 v1, v20, v1
	v_readlane_b32 s13, v253, 58
	v_mul_lo_u32 v2, v1, s2
	v_mul_lo_u32 v1, v1, s4
	s_mul_i32 s4, s8, s13
	s_mul_hi_u32 s5, s8, s12
	s_add_i32 s10, s5, s4
	s_lshr_b64 s[4:5], s[2:3], 23
	s_ashr_i32 s1, s14, 6
	s_mul_i32 s4, s4, s12
	s_ashr_i32 s0, s14, 8
	s_lshl_b64 s[6:7], s[2:3], 8
	s_lshl_b32 s26, s1, 10
	v_ashrrev_i16_sdwa v0, v4, sext(v0) dst_sel:DWORD dst_unused:UNUSED_PAD src0_sel:DWORD src1_sel:BYTE_0
	s_add_i32 s10, s10, s4
	s_mul_i32 s4, s8, s12
	v_bfe_i32 v19, v0, 0, 16
	s_add_u32 s20, s24, s4
	v_add_u32_e32 v0, v17, v19
	s_addc_u32 s21, s25, s10
	s_add_i32 s27, s26, 0
	v_add_lshl_u32 v176, v0, v2, 1
	s_add_i32 m0, s27, 0x10000
	v_readlane_b32 s4, v254, 15
	global_load_lds_dwordx4 v176, s[20:21]
	s_add_i32 m0, s27, 0x12000
	s_mov_b32 s10, s4
	s_mul_i32 s4, s4, 0x160000
	s_add_u32 s18, s22, s4
	s_mul_hi_i32 s4, s10, 0x160000
	s_addc_u32 s19, s23, s4
	v_readlane_b32 s5, v254, 16
	s_add_u32 s4, s20, s6
	global_load_lds_dwordx4 v144, s[20:21]
	s_addc_u32 s5, s21, s7
	s_add_i32 m0, s27, 0x14000
	v_mov_b32_e32 v145, v177
	global_load_lds_dwordx4 v176, s[4:5]
	s_add_i32 m0, s27, 0x16000
	s_add_i32 s28, s27, 0x2000
	v_add_lshl_u32 v148, v0, v1, 1
	v_lshl_add_u64 v[4:5], s[4:5], 0, v[176:177]
	v_lshl_add_u64 v[6:7], s[4:5], 0, v[144:145]
	global_load_lds_dwordx4 v144, s[4:5]
	s_mov_b32 m0, s27
	s_add_u32 s4, s18, 0xb0000
	global_load_lds_dwordx4 v148, s[18:19]
	s_mov_b32 m0, s28
	s_addc_u32 s5, s19, 0
	s_add_i32 s29, s27, 0x4000
	global_load_lds_dwordx4 v146, s[18:19]
	s_mov_b32 m0, s29
	s_add_i32 s30, s27, 0x6000
	global_load_lds_dwordx4 v148, s[4:5]
	s_mov_b32 m0, s30
	v_mov_b32_e32 v149, v177
	global_load_lds_dwordx4 v146, s[4:5]
	v_mov_b32_e32 v147, v177
	s_cmp_eq_u32 s0, 1
	v_lshl_add_u64 v[0:1], s[20:21], 0, v[176:177]
	v_lshl_add_u64 v[2:3], s[20:21], 0, v[144:145]
	v_lshl_add_u64 v[8:9], s[18:19], 0, v[148:149]
	v_lshl_add_u64 v[10:11], s[18:19], 0, v[146:147]
	s_cselect_b64 s[10:11], -1, 0
	s_cmp_lg_u32 s0, 1
	s_cbranch_scc1 .LBB0_1601
	s_barrier

.LBB0_1624:
	s_mov_b64 s[0:1], 0x80000
	s_setprio 0
	s_getreg_b32 s6, hwreg(HW_REG_XCC_ID, 0, 4)
	s_waitcnt vmcnt(0)
	s_waitcnt lgkmcnt(0)
	s_barrier
	s_getreg_b32 s2, hwreg(HW_REG_HW_ID, 0, 6)
	s_and_b32 s2, s2, 63
	s_lshl_b32 s2, s2, 2
	s_add_i32 s2, s2, 0
	s_add_i32 s2, s2, 0x22ef0
	v_mov_b32_e32 v0, s2
	ds_read_b32 v0, v0
	s_waitcnt lgkmcnt(0)
	v_readfirstlane_b32 s2, v0
	v_mov_b32_e32 v0, v177
	s_nop 0
	v_mbcnt_lo_u32_b32 v0, -1, v0
	v_mbcnt_hi_u32_b32 v0, -1, v0
	v_lshl_add_u32 v0, s2, 6, v0
	s_nop 0
	v_cmp_eq_u32_e32 vcc, 0, v0
	s_and_saveexec_b64 s[2:3], vcc
	s_cbranch_execnz .LBB0_1625
	s_getpc_b64 s[98:99]
